# w_ffn2_out transposes moved into the phase-1 tail queue; GLA loop at its better placement; padding totals 128 bytes so later code keeps its 128-byte phase
# baseline (speedup 1.0000x reference)
; #define BAR_LDS() do { asm volatile("s_waitcnt lgkmcnt(0)" ::: "memory"); __builtin_amdgcn_s_barrier(); asm volatile("" ::: "memory"); } while (0)
; __device__ __forceinline__ void gla_item(const Params& p, unsigned char* sm, int h, int job0, int jobstride, int nchunks, int tok0, int nvalid, const float* s_init, float* s_out, const int TIDX) {
;     ...
;         if (ci + 1 < nchunks) { GLA_STORE(); }
;         BAR_LDS();
;     }
.LBB0_173:
	s_or_b64 exec, exec, vcc
	s_branch .Lgla_next
	s_nop 0
	s_nop 0
	s_nop 0
	s_nop 0
	s_nop 0
	s_nop 0
	s_nop 0
	s_nop 0
	s_nop 0
	s_nop 0
	s_nop 0
	s_nop 0
	s_nop 0
	s_nop 0
	s_nop 0
	s_nop 0
	s_nop 0
	s_nop 0
	s_nop 0
	s_nop 0
